# P2 gelu(v) transposed store via wave-private LDS pieces and coalesced dwordx4 stores, on top of previous stack
# baseline (speedup 1.0000x reference)
.LBB0_516:
	s_andn2_b64 vcc, exec, s[2:3]
	s_cbranch_vccnz .LBB0_550
	v_lshrrev_b32_e32 v85, 4, v214
	v_and_b32_e32 v85, 3, v85
	v_and_b32_e32 v86, 15, v214
	v_lshrrev_b32_e32 v87, 6, v215
	v_lshlrev_b32_e32 v84, 13, v85
	v_lshl_add_u32 v84, v87, 10, v84
	v_lshl_add_u32 v84, v86, 1, v84
	s_waitcnt vmcnt(8)
	v_and_b32_e32 v65, 64, v182
	v_xor_b32_e32 v64, 16, v182
	v_add_u32_e32 v67, 64, v65
	v_cmp_lt_i32_e32 vcc, v64, v67
	v_and_b32_e32 v65, 0x7fffffff, v61
	v_mov_b64_e32 v[78:79], s[48:49]
	v_cndmask_b32_e32 v68, v182, v64, vcc
	v_and_b32_e32 v64, 0x7fffffff, v60
	v_pk_fma_f32 v[64:65], v[64:65], s[90:91], 1.0 op_sel_hi:[1,0,0]
	v_pk_mul_f32 v[72:73], v[60:61], v[60:61]
	v_rcp_f32_e32 v64, v64
	v_rcp_f32_e32 v65, v65
	v_lshlrev_b32_e32 v70, 2, v68
	v_pk_mul_f32 v[72:73], v[72:73], s[66:67] op_sel_hi:[1,0]
	v_cmp_gt_f32_e32 vcc, 0, v60
	v_pk_fma_f32 v[68:69], v[64:65], s[92:93], v[78:79] op_sel_hi:[1,0,0]
	v_exp_f32_e32 v72, v72
	v_pk_fma_f32 v[68:69], v[64:65], v[68:69], s[96:97] op_sel_hi:[1,1,0]
	v_exp_f32_e32 v73, v73
	v_pk_fma_f32 v[68:69], v[64:65], v[68:69], s[12:13] op_sel_hi:[1,1,0]
	v_pk_mul_f32 v[74:75], v[62:63], v[62:63]
	v_pk_fma_f32 v[68:69], v[64:65], v[68:69], s[14:15] op_sel_hi:[1,1,0]
	v_pk_mul_f32 v[74:75], v[74:75], s[66:67] op_sel_hi:[1,0]
	v_pk_mul_f32 v[64:65], v[64:65], v[68:69]
	v_exp_f32_e32 v74, v74
	v_pk_mul_f32 v[64:65], v[72:73], v[64:65]
	v_and_b32_e32 v73, 0x7fffffff, v63
	v_and_b32_e32 v72, 0x7fffffff, v62
	v_pk_fma_f32 v[72:73], v[72:73], s[90:91], 1.0 op_sel_hi:[1,0,0]
	v_pk_mul_f32 v[68:69], v[60:61], v[64:65]
	v_rcp_f32_e32 v76, v72
	v_rcp_f32_e32 v77, v73
	v_pk_fma_f32 v[64:65], v[60:61], v[64:65], v[60:61] neg_lo:[1,0,0] neg_hi:[1,0,0]
	v_exp_f32_e32 v75, v75
	v_cndmask_b32_e32 v72, v64, v68, vcc
	v_cmp_gt_f32_e32 vcc, 0, v61
	v_pk_mul_f32 v[80:81], v[58:59], v[58:59]
	v_xor_b32_e32 v71, 32, v182
	v_cndmask_b32_e32 v69, v65, v69, vcc
	v_pk_fma_f32 v[64:65], v[76:77], s[92:93], v[78:79] op_sel_hi:[1,0,0]
	v_cmp_gt_f32_e32 vcc, 0, v62
	v_pk_fma_f32 v[64:65], v[76:77], v[64:65], s[96:97] op_sel_hi:[1,1,0]
	s_add_i32 s17, s17, -4
	v_pk_fma_f32 v[64:65], v[76:77], v[64:65], s[12:13] op_sel_hi:[1,1,0]
	s_lshl_b32 s80, s17, 1
	v_pk_fma_f32 v[64:65], v[76:77], v[64:65], s[14:15] op_sel_hi:[1,1,0]
	s_lshl_b64 s[2:3], s[80:81], 2
	v_pk_mul_f32 v[64:65], v[76:77], v[64:65]
	v_and_b32_e32 v77, 0x7fffffff, v57
	v_and_b32_e32 v76, 0x7fffffff, v56
	v_pk_fma_f32 v[76:77], v[76:77], s[90:91], 1.0 op_sel_hi:[1,0,0]
	v_pk_mul_f32 v[64:65], v[74:75], v[64:65]
	v_rcp_f32_e32 v76, v76
	v_rcp_f32_e32 v77, v77
	v_pk_mul_f32 v[74:75], v[62:63], v[64:65]
	v_pk_fma_f32 v[64:65], v[62:63], v[64:65], v[62:63] neg_lo:[1,0,0] neg_hi:[1,0,0]
	v_lshl_add_u32 v66, s10, 8, v170
	v_cndmask_b32_e32 v73, v64, v74, vcc
	v_cmp_gt_f32_e32 vcc, 0, v63
	s_add_u32 s8, s82, s2
	s_addc_u32 s9, s83, s3
	v_cndmask_b32_e32 v68, v65, v75, vcc
	v_pk_fma_f32 v[64:65], v[76:77], s[92:93], v[78:79] op_sel_hi:[1,0,0]
	v_pk_mul_f32 v[74:75], v[56:57], v[56:57]
	v_pk_fma_f32 v[64:65], v[76:77], v[64:65], s[96:97] op_sel_hi:[1,1,0]
	v_pk_mul_f32 v[74:75], v[74:75], s[66:67] op_sel_hi:[1,0]
	v_pk_fma_f32 v[64:65], v[76:77], v[64:65], s[12:13] op_sel_hi:[1,1,0]
	v_exp_f32_e32 v74, v74
	v_exp_f32_e32 v75, v75
	v_pk_fma_f32 v[64:65], v[76:77], v[64:65], s[14:15] op_sel_hi:[1,1,0]
	v_cmp_gt_f32_e32 vcc, 0, v56
	v_pk_mul_f32 v[64:65], v[76:77], v[64:65]
	v_and_b32_e32 v77, 0x7fffffff, v59
	v_and_b32_e32 v76, 0x7fffffff, v58
	v_pk_fma_f32 v[76:77], v[76:77], s[90:91], 1.0 op_sel_hi:[1,0,0]
	v_pk_mul_f32 v[64:65], v[74:75], v[64:65]
	v_rcp_f32_e32 v82, v76
	v_rcp_f32_e32 v83, v77
	v_pk_mul_f32 v[74:75], v[56:57], v[64:65]
	v_pk_fma_f32 v[64:65], v[56:57], v[64:65], v[56:57] neg_lo:[1,0,0] neg_hi:[1,0,0]
	s_nop 0
	v_cndmask_b32_e32 v77, v64, v74, vcc
	v_cmp_gt_f32_e32 vcc, 0, v57
	s_nop 1
	v_cndmask_b32_e32 v75, v65, v75, vcc
	v_pk_fma_f32 v[64:65], v[82:83], s[92:93], v[78:79] op_sel_hi:[1,0,0]
	v_pk_mul_f32 v[78:79], v[80:81], s[66:67] op_sel_hi:[1,0]
	v_pk_fma_f32 v[64:65], v[82:83], v[64:65], s[96:97] op_sel_hi:[1,1,0]
	v_exp_f32_e32 v78, v78
	v_exp_f32_e32 v79, v79
	v_pk_fma_f32 v[64:65], v[82:83], v[64:65], s[12:13] op_sel_hi:[1,1,0]
	v_cmp_gt_f32_e32 vcc, 0, v58
	v_pk_fma_f32 v[64:65], v[82:83], v[64:65], s[14:15] op_sel_hi:[1,1,0]
	s_nop 0
	v_pk_mul_f32 v[64:65], v[82:83], v[64:65]
	s_nop 0
	v_pk_mul_f32 v[64:65], v[78:79], v[64:65]
	s_nop 0
	v_pk_mul_f32 v[78:79], v[58:59], v[64:65]
	v_pk_fma_f32 v[64:65], v[58:59], v[64:65], v[58:59] neg_lo:[1,0,0] neg_hi:[1,0,0]
	s_nop 0
	v_cndmask_b32_e32 v76, v64, v78, vcc
	v_cmp_gt_f32_e32 vcc, 0, v59
	v_mul_f32_e32 v64, v69, v69
	v_fmac_f32_e32 v64, v72, v72
	v_cndmask_b32_e32 v74, v65, v79, vcc
	v_mul_f32_e32 v65, v68, v68
	v_fmac_f32_e32 v65, v73, v73
	v_add_f32_e32 v64, v64, v65
	v_mul_f32_e32 v65, v75, v75
	v_mul_f32_e32 v78, v74, v74
	v_fmac_f32_e32 v65, v77, v77
	v_fmac_f32_e32 v78, v76, v76
	v_add_f32_e32 v65, v65, v78
	v_add_f32_e32 v64, v64, v65
	ds_bpermute_b32 v65, v70, v64
	v_cmp_lt_i32_e32 vcc, v71, v67
	s_waitcnt lgkmcnt(0)
	v_add_f32_e32 v64, v64, v65
	v_cndmask_b32_e32 v67, v182, v71, vcc
	v_lshlrev_b32_e32 v71, 2, v67
	ds_bpermute_b32 v65, v71, v64
	v_ashrrev_i32_e32 v67, 31, v66
	s_and_saveexec_b64 s[2:3], s[4:5]
	s_xor_b64 s[2:3], exec, s[2:3]
	s_andn2_saveexec_b64 s[2:3], s[2:3]
	s_cbranch_execz .LBB0_521
	s_waitcnt lgkmcnt(0)
	v_add_f32_e32 v78, v64, v65
	v_mov_b64_e32 v[64:65], s[8:9]
	v_mad_i64_i32 v[64:65], s[34:35], v66, s18, v[64:65]
	s_lshl_b32 s80, s15, 2
	v_lshl_add_u64 v[64:65], v[64:65], 0, s[80:81]
	global_store_dword v[64:65], v78, off offset:80
.LBB0_521:
	s_or_b64 exec, exec, s[2:3]
	v_lshl_or_b32 v144, s17, 6, v152
	v_readlane_b32 s2, v252, 0
	s_waitcnt lgkmcnt(0)
	v_lshlrev_b64 v[64:65], 14, v[144:145]
	v_readlane_b32 s3, v252, 1
	s_mov_b32 s16, 0xbf3a00e3
	v_pk_mul_f32 v[82:83], v[48:49], v[48:49]
	v_lshl_add_u64 v[64:65], s[2:3], 0, v[64:65]
	v_lshl_add_u64 v[78:79], v[66:67], 1, v[64:65]
	v_bfe_u32 v67, v72, 16, 1
	v_add3_u32 v67, v72, v67, s33
	ds_write_b16_d16_hi v84, v67 offset:0
	v_bfe_u32 v67, v77, 16, 1
	v_add_co_u32_e32 v80, vcc, 0x10000, v78
	v_add3_u32 v67, v77, v67, s33
	s_nop 0
	v_addc_co_u32_e32 v81, vcc, 0, v79, vcc
	ds_write_b16_d16_hi v84, v67 offset:512
	v_bfe_u32 v67, v69, 16, 1
	v_add_co_u32_e32 v80, vcc, 0x4000, v78
	v_add3_u32 v67, v69, v67, s33
	s_nop 0
	v_addc_co_u32_e32 v81, vcc, 0, v79, vcc
	ds_write_b16_d16_hi v84, v67 offset:128
	v_bfe_u32 v67, v75, 16, 1
	v_add_co_u32_e32 v80, vcc, 0x14000, v78
	v_add3_u32 v67, v75, v67, s33
	s_nop 0
	v_addc_co_u32_e32 v81, vcc, 0, v79, vcc
	ds_write_b16_d16_hi v84, v67 offset:640
	v_bfe_u32 v67, v73, 16, 1
	v_add_co_u32_e32 v72, vcc, 0x8000, v78
	v_add3_u32 v67, v73, v67, s33
	s_nop 0
	v_addc_co_u32_e32 v73, vcc, 0, v79, vcc
	ds_write_b16_d16_hi v84, v67 offset:256
	v_bfe_u32 v67, v76, 16, 1
	v_add_co_u32_e32 v72, vcc, 0x18000, v78
	v_add3_u32 v67, v76, v67, s33
	s_nop 0
	v_addc_co_u32_e32 v73, vcc, 0, v79, vcc
	ds_write_b16_d16_hi v84, v67 offset:768
	v_and_b32_e32 v73, 0x7fffffff, v53
	v_and_b32_e32 v72, 0x7fffffff, v52
	v_bfe_u32 v67, v68, 16, 1
	v_pk_fma_f32 v[72:73], v[72:73], s[90:91], 1.0 op_sel_hi:[1,0,0]
	v_add3_u32 v67, v68, v67, s33
	v_add_co_u32_e32 v68, vcc, 0xc000, v78
	v_rcp_f32_e32 v72, v72
	v_rcp_f32_e32 v73, v73
	v_addc_co_u32_e32 v69, vcc, 0, v79, vcc
	ds_write_b16_d16_hi v84, v67 offset:384
	v_add_co_u32_e32 v68, vcc, 0x1c000, v78
	v_bfe_u32 v67, v74, 16, 1
	s_nop 0
	v_addc_co_u32_e32 v69, vcc, 0, v79, vcc
	v_mov_b64_e32 v[78:79], s[16:17]
	v_pk_mul_f32 v[76:77], v[52:53], v[52:53]
	v_add3_u32 v67, v74, v67, s33
	v_pk_fma_f32 v[74:75], v[72:73], s[92:93], v[78:79] op_sel_hi:[1,0,0]
	v_pk_mul_f32 v[76:77], v[76:77], s[66:67] op_sel_hi:[1,0]
	v_pk_fma_f32 v[74:75], v[72:73], v[74:75], s[96:97] op_sel_hi:[1,1,0]
	v_exp_f32_e32 v76, v76
	v_exp_f32_e32 v77, v77
	v_pk_fma_f32 v[74:75], v[72:73], v[74:75], s[12:13] op_sel_hi:[1,1,0]
	v_cmp_gt_f32_e32 vcc, 0, v52
	v_pk_fma_f32 v[74:75], v[72:73], v[74:75], s[14:15] op_sel_hi:[1,1,0]
	ds_write_b16_d16_hi v84, v67 offset:896
	v_pk_mul_f32 v[72:73], v[72:73], v[74:75]
	v_pk_mul_f32 v[74:75], v[54:55], v[54:55]
	v_pk_mul_f32 v[72:73], v[76:77], v[72:73]
	v_pk_mul_f32 v[74:75], v[74:75], s[66:67] op_sel_hi:[1,0]
	v_pk_mul_f32 v[76:77], v[52:53], v[72:73]
	v_pk_fma_f32 v[72:73], v[52:53], v[72:73], v[52:53] neg_lo:[1,0,0] neg_hi:[1,0,0]
	v_exp_f32_e32 v74, v74
	v_cndmask_b32_e32 v72, v72, v76, vcc
	v_cmp_gt_f32_e32 vcc, 0, v53
	v_and_b32_e32 v76, 0x7fffffff, v54
	v_exp_f32_e32 v75, v75
	v_cndmask_b32_e32 v67, v73, v77, vcc
	v_and_b32_e32 v77, 0x7fffffff, v55
	v_pk_fma_f32 v[76:77], v[76:77], s[90:91], 1.0 op_sel_hi:[1,0,0]
	v_cmp_gt_f32_e32 vcc, 0, v54
	v_rcp_f32_e32 v76, v76
	v_rcp_f32_e32 v77, v77
	v_pk_mul_f32 v[82:83], v[82:83], s[66:67] op_sel_hi:[1,0]
	v_mul_f32_e32 v69, v67, v67
	v_exp_f32_e32 v82, v82
	v_pk_fma_f32 v[80:81], v[76:77], s[92:93], v[78:79] op_sel_hi:[1,0,0]
	v_exp_f32_e32 v83, v83
	v_pk_fma_f32 v[80:81], v[76:77], v[80:81], s[96:97] op_sel_hi:[1,1,0]
	v_fmac_f32_e32 v69, v72, v72
	v_pk_fma_f32 v[80:81], v[76:77], v[80:81], s[12:13] op_sel_hi:[1,1,0]
	v_or_b32_e32 v68, 16, v66
	v_pk_fma_f32 v[80:81], v[76:77], v[80:81], s[14:15] op_sel_hi:[1,1,0]
	s_nop 0
	v_pk_mul_f32 v[76:77], v[76:77], v[80:81]
	s_nop 0
	v_pk_mul_f32 v[74:75], v[74:75], v[76:77]
	s_nop 0
	v_pk_mul_f32 v[76:77], v[54:55], v[74:75]
	v_pk_fma_f32 v[74:75], v[54:55], v[74:75], v[54:55] neg_lo:[1,0,0] neg_hi:[1,0,0]
	s_nop 0
	v_cndmask_b32_e32 v74, v74, v76, vcc
	v_cmp_gt_f32_e32 vcc, 0, v55
	v_and_b32_e32 v76, 0x7fffffff, v48
	s_nop 0
	v_cndmask_b32_e32 v73, v75, v77, vcc
	v_and_b32_e32 v77, 0x7fffffff, v49
	v_pk_fma_f32 v[76:77], v[76:77], s[90:91], 1.0 op_sel_hi:[1,0,0]
	v_cmp_gt_f32_e32 vcc, 0, v48
	v_rcp_f32_e32 v76, v76
	v_rcp_f32_e32 v77, v77
	s_nop 0
	v_pk_fma_f32 v[80:81], v[76:77], s[92:93], v[78:79] op_sel_hi:[1,0,0]
	s_nop 0
	v_pk_fma_f32 v[80:81], v[76:77], v[80:81], s[96:97] op_sel_hi:[1,1,0]
	s_nop 0
	v_pk_fma_f32 v[80:81], v[76:77], v[80:81], s[12:13] op_sel_hi:[1,1,0]
	s_nop 0
	v_pk_fma_f32 v[80:81], v[76:77], v[80:81], s[14:15] op_sel_hi:[1,1,0]
	s_nop 0
	v_pk_mul_f32 v[76:77], v[76:77], v[80:81]
	v_pk_mul_f32 v[80:81], v[50:51], v[50:51]
	v_pk_mul_f32 v[76:77], v[82:83], v[76:77]
	v_pk_mul_f32 v[80:81], v[80:81], s[66:67] op_sel_hi:[1,0]
	v_pk_mul_f32 v[82:83], v[48:49], v[76:77]
	v_pk_fma_f32 v[76:77], v[48:49], v[76:77], v[48:49] neg_lo:[1,0,0] neg_hi:[1,0,0]
	v_exp_f32_e32 v80, v80
	v_cndmask_b32_e32 v76, v76, v82, vcc
	v_cmp_gt_f32_e32 vcc, 0, v49
	v_and_b32_e32 v82, 0x7fffffff, v50
	v_exp_f32_e32 v81, v81
	v_cndmask_b32_e32 v75, v77, v83, vcc
	v_and_b32_e32 v83, 0x7fffffff, v51
	v_pk_fma_f32 v[82:83], v[82:83], s[90:91], 1.0 op_sel_hi:[1,0,0]
	v_cmp_gt_f32_e32 vcc, 0, v50
	v_rcp_f32_e32 v82, v82
	v_rcp_f32_e32 v83, v83
	s_nop 0
	v_pk_fma_f32 v[78:79], v[82:83], s[92:93], v[78:79] op_sel_hi:[1,0,0]
	s_nop 0
	v_pk_fma_f32 v[78:79], v[82:83], v[78:79], s[96:97] op_sel_hi:[1,1,0]
	s_nop 0
	v_pk_fma_f32 v[78:79], v[82:83], v[78:79], s[12:13] op_sel_hi:[1,1,0]
	s_nop 0
	v_pk_fma_f32 v[78:79], v[82:83], v[78:79], s[14:15] op_sel_hi:[1,1,0]
	s_nop 0
	v_pk_mul_f32 v[78:79], v[82:83], v[78:79]
	s_nop 0
	v_pk_mul_f32 v[78:79], v[80:81], v[78:79]
	s_nop 0
	v_pk_mul_f32 v[80:81], v[50:51], v[78:79]
	v_pk_fma_f32 v[78:79], v[50:51], v[78:79], v[50:51] neg_lo:[1,0,0] neg_hi:[1,0,0]
	s_nop 0
	v_cndmask_b32_e32 v78, v78, v80, vcc
	v_cmp_gt_f32_e32 vcc, 0, v51
	s_nop 1
	v_cndmask_b32_e32 v77, v79, v81, vcc
	v_mul_f32_e32 v79, v73, v73
	v_fmac_f32_e32 v79, v74, v74
	v_add_f32_e32 v69, v69, v79
	v_mul_f32_e32 v79, v75, v75
	v_mul_f32_e32 v80, v77, v77
	v_fmac_f32_e32 v79, v76, v76
	v_fmac_f32_e32 v80, v78, v78
	v_add_f32_e32 v79, v79, v80
	v_add_f32_e32 v69, v69, v79
	ds_bpermute_b32 v79, v70, v69
	s_waitcnt lgkmcnt(0)
	v_add_f32_e32 v79, v69, v79
	ds_bpermute_b32 v80, v71, v79
	v_ashrrev_i32_e32 v69, 31, v68
	s_and_saveexec_b64 s[2:3], s[4:5]
	s_xor_b64 s[2:3], exec, s[2:3]
	s_andn2_saveexec_b64 s[2:3], s[2:3]
	s_cbranch_execz .LBB0_525
	s_waitcnt lgkmcnt(0)
	v_add_f32_e32 v79, v79, v80
	v_mov_b64_e32 v[80:81], s[8:9]
	v_mad_i64_i32 v[80:81], s[34:35], v68, s18, v[80:81]
	s_lshl_b32 s80, s15, 2
	v_lshl_add_u64 v[80:81], v[80:81], 0, s[80:81]
	global_store_dword v[80:81], v79, off offset:80
.LBB0_525:
	s_or_b64 exec, exec, s[2:3]
	v_bfe_u32 v79, v72, 16, 1
	v_lshl_add_u64 v[68:69], v[68:69], 1, v[64:65]
	v_add3_u32 v72, v72, v79, s33
	ds_write_b16_d16_hi v84, v72 offset:32
	v_bfe_u32 v72, v76, 16, 1
	s_waitcnt lgkmcnt(0)
	v_add_co_u32_e32 v80, vcc, 0x10000, v68
	v_add3_u32 v72, v76, v72, s33
	s_nop 0
	v_addc_co_u32_e32 v81, vcc, 0, v69, vcc
	ds_write_b16_d16_hi v84, v72 offset:544
	v_bfe_u32 v72, v67, 16, 1
	v_add_co_u32_e32 v80, vcc, 0x4000, v68
	v_add3_u32 v67, v67, v72, s33
	s_nop 0
	v_addc_co_u32_e32 v81, vcc, 0, v69, vcc
	ds_write_b16_d16_hi v84, v67 offset:160
	v_bfe_u32 v67, v75, 16, 1
	v_add_co_u32_e32 v80, vcc, 0x14000, v68
	v_add3_u32 v67, v75, v67, s33
	s_nop 0
	v_addc_co_u32_e32 v81, vcc, 0, v69, vcc
	ds_write_b16_d16_hi v84, v67 offset:672
	v_bfe_u32 v67, v74, 16, 1
	v_add3_u32 v67, v74, v67, s33
	v_add_co_u32_e32 v74, vcc, 0x8000, v68
	v_pk_mul_f32 v[82:83], v[40:41], v[40:41]
	s_nop 0
	v_addc_co_u32_e32 v75, vcc, 0, v69, vcc
	ds_write_b16_d16_hi v84, v67 offset:288
	v_bfe_u32 v67, v78, 16, 1
	v_add_co_u32_e32 v74, vcc, 0x18000, v68
	v_add3_u32 v67, v78, v67, s33
	s_nop 0
	v_addc_co_u32_e32 v75, vcc, 0, v69, vcc
	ds_write_b16_d16_hi v84, v67 offset:800
	v_bfe_u32 v67, v73, 16, 1
	v_add_co_u32_e32 v72, vcc, 0xc000, v68
	v_add3_u32 v67, v73, v67, s33
	s_nop 0
	v_addc_co_u32_e32 v73, vcc, 0, v69, vcc
	ds_write_b16_d16_hi v84, v67 offset:416
	v_and_b32_e32 v73, 0x7fffffff, v45
	v_and_b32_e32 v72, 0x7fffffff, v44
	v_pk_fma_f32 v[72:73], v[72:73], s[90:91], 1.0 op_sel_hi:[1,0,0]
	v_bfe_u32 v67, v77, 16, 1
	v_rcp_f32_e32 v72, v72
	v_rcp_f32_e32 v73, v73
	v_add3_u32 v67, v77, v67, s33
	v_mov_b64_e32 v[78:79], s[16:17]
	v_pk_mul_f32 v[76:77], v[44:45], v[44:45]
	v_pk_fma_f32 v[74:75], v[72:73], s[92:93], v[78:79] op_sel_hi:[1,0,0]
	v_pk_mul_f32 v[76:77], v[76:77], s[66:67] op_sel_hi:[1,0]
	v_pk_fma_f32 v[74:75], v[72:73], v[74:75], s[96:97] op_sel_hi:[1,1,0]
	v_exp_f32_e32 v76, v76
	v_exp_f32_e32 v77, v77
	v_pk_fma_f32 v[74:75], v[72:73], v[74:75], s[12:13] op_sel_hi:[1,1,0]
	v_add_co_u32_e32 v68, vcc, 0x1c000, v68
	v_pk_fma_f32 v[74:75], v[72:73], v[74:75], s[14:15] op_sel_hi:[1,1,0]
	s_nop 0
	v_addc_co_u32_e32 v69, vcc, 0, v69, vcc
	v_pk_mul_f32 v[72:73], v[72:73], v[74:75]
	v_cmp_gt_f32_e32 vcc, 0, v44
	v_pk_mul_f32 v[72:73], v[76:77], v[72:73]
	ds_write_b16_d16_hi v84, v67 offset:928
	v_pk_mul_f32 v[76:77], v[44:45], v[72:73]
	v_pk_fma_f32 v[72:73], v[44:45], v[72:73], v[44:45] neg_lo:[1,0,0] neg_hi:[1,0,0]
	v_pk_mul_f32 v[74:75], v[46:47], v[46:47]
	v_cndmask_b32_e32 v72, v72, v76, vcc
	v_cmp_gt_f32_e32 vcc, 0, v45
	v_and_b32_e32 v76, 0x7fffffff, v46
	v_pk_mul_f32 v[74:75], v[74:75], s[66:67] op_sel_hi:[1,0]
	v_cndmask_b32_e32 v67, v73, v77, vcc
	v_and_b32_e32 v77, 0x7fffffff, v47
	v_pk_fma_f32 v[76:77], v[76:77], s[90:91], 1.0 op_sel_hi:[1,0,0]
	v_exp_f32_e32 v74, v74
	v_rcp_f32_e32 v76, v76
	v_rcp_f32_e32 v77, v77
	v_exp_f32_e32 v75, v75
	v_cmp_gt_f32_e32 vcc, 0, v46
	v_pk_mul_f32 v[82:83], v[82:83], s[66:67] op_sel_hi:[1,0]
	v_pk_fma_f32 v[80:81], v[76:77], s[92:93], v[78:79] op_sel_hi:[1,0,0]
	v_exp_f32_e32 v82, v82
	v_pk_fma_f32 v[80:81], v[76:77], v[80:81], s[96:97] op_sel_hi:[1,1,0]
	v_exp_f32_e32 v83, v83
	v_pk_fma_f32 v[80:81], v[76:77], v[80:81], s[12:13] op_sel_hi:[1,1,0]
	v_mul_f32_e32 v69, v67, v67
	v_pk_fma_f32 v[80:81], v[76:77], v[80:81], s[14:15] op_sel_hi:[1,1,0]
	v_fmac_f32_e32 v69, v72, v72
	v_pk_mul_f32 v[76:77], v[76:77], v[80:81]
	v_or_b32_e32 v68, 32, v66
	v_pk_mul_f32 v[74:75], v[74:75], v[76:77]
	s_nop 0
	v_pk_mul_f32 v[76:77], v[46:47], v[74:75]
	v_pk_fma_f32 v[74:75], v[46:47], v[74:75], v[46:47] neg_lo:[1,0,0] neg_hi:[1,0,0]
	s_nop 0
	v_cndmask_b32_e32 v74, v74, v76, vcc
	v_cmp_gt_f32_e32 vcc, 0, v47
	v_and_b32_e32 v76, 0x7fffffff, v40
	s_nop 0
	v_cndmask_b32_e32 v73, v75, v77, vcc
	v_and_b32_e32 v77, 0x7fffffff, v41
	v_pk_fma_f32 v[76:77], v[76:77], s[90:91], 1.0 op_sel_hi:[1,0,0]
	v_cmp_gt_f32_e32 vcc, 0, v40
	v_rcp_f32_e32 v76, v76
	v_rcp_f32_e32 v77, v77
	s_nop 0
	v_pk_fma_f32 v[80:81], v[76:77], s[92:93], v[78:79] op_sel_hi:[1,0,0]
	s_nop 0
	v_pk_fma_f32 v[80:81], v[76:77], v[80:81], s[96:97] op_sel_hi:[1,1,0]
	s_nop 0
	v_pk_fma_f32 v[80:81], v[76:77], v[80:81], s[12:13] op_sel_hi:[1,1,0]
	s_nop 0
	v_pk_fma_f32 v[80:81], v[76:77], v[80:81], s[14:15] op_sel_hi:[1,1,0]
	s_nop 0
	v_pk_mul_f32 v[76:77], v[76:77], v[80:81]
	v_pk_mul_f32 v[80:81], v[42:43], v[42:43]
	v_pk_mul_f32 v[76:77], v[82:83], v[76:77]
	v_pk_mul_f32 v[80:81], v[80:81], s[66:67] op_sel_hi:[1,0]
	v_pk_mul_f32 v[82:83], v[40:41], v[76:77]
	v_pk_fma_f32 v[76:77], v[40:41], v[76:77], v[40:41] neg_lo:[1,0,0] neg_hi:[1,0,0]
	v_exp_f32_e32 v80, v80
	v_cndmask_b32_e32 v76, v76, v82, vcc
	v_cmp_gt_f32_e32 vcc, 0, v41
	v_and_b32_e32 v82, 0x7fffffff, v42
	v_exp_f32_e32 v81, v81
	v_cndmask_b32_e32 v75, v77, v83, vcc
	v_and_b32_e32 v83, 0x7fffffff, v43
	v_pk_fma_f32 v[82:83], v[82:83], s[90:91], 1.0 op_sel_hi:[1,0,0]
	v_cmp_gt_f32_e32 vcc, 0, v42
	v_rcp_f32_e32 v82, v82
	v_rcp_f32_e32 v83, v83
	s_nop 0
	v_pk_fma_f32 v[78:79], v[82:83], s[92:93], v[78:79] op_sel_hi:[1,0,0]
	s_nop 0
	v_pk_fma_f32 v[78:79], v[82:83], v[78:79], s[96:97] op_sel_hi:[1,1,0]
	s_nop 0
	v_pk_fma_f32 v[78:79], v[82:83], v[78:79], s[12:13] op_sel_hi:[1,1,0]
	s_nop 0
	v_pk_fma_f32 v[78:79], v[82:83], v[78:79], s[14:15] op_sel_hi:[1,1,0]
	s_nop 0
	v_pk_mul_f32 v[78:79], v[82:83], v[78:79]
	s_nop 0
	v_pk_mul_f32 v[78:79], v[80:81], v[78:79]
	s_nop 0
	v_pk_mul_f32 v[80:81], v[42:43], v[78:79]
	v_pk_fma_f32 v[78:79], v[42:43], v[78:79], v[42:43] neg_lo:[1,0,0] neg_hi:[1,0,0]
	s_nop 0
	v_cndmask_b32_e32 v78, v78, v80, vcc
	v_cmp_gt_f32_e32 vcc, 0, v43
	s_nop 1
	v_cndmask_b32_e32 v77, v79, v81, vcc
	v_mul_f32_e32 v79, v73, v73
	v_fmac_f32_e32 v79, v74, v74
	v_add_f32_e32 v69, v69, v79
	v_mul_f32_e32 v79, v75, v75
	v_mul_f32_e32 v80, v77, v77
	v_fmac_f32_e32 v79, v76, v76
	v_fmac_f32_e32 v80, v78, v78
	v_add_f32_e32 v79, v79, v80
	v_add_f32_e32 v69, v69, v79
	ds_bpermute_b32 v79, v70, v69
	s_waitcnt lgkmcnt(0)
	v_add_f32_e32 v79, v69, v79
	ds_bpermute_b32 v80, v71, v79
	v_ashrrev_i32_e32 v69, 31, v68
	s_and_saveexec_b64 s[2:3], s[4:5]
	s_xor_b64 s[2:3], exec, s[2:3]
	s_andn2_saveexec_b64 s[2:3], s[2:3]
	s_cbranch_execz .LBB0_529
	s_waitcnt lgkmcnt(0)
	v_add_f32_e32 v79, v79, v80
	v_mov_b64_e32 v[80:81], s[8:9]
	v_mad_i64_i32 v[80:81], s[34:35], v68, s18, v[80:81]
	s_lshl_b32 s80, s15, 2
	v_lshl_add_u64 v[80:81], v[80:81], 0, s[80:81]
	global_store_dword v[80:81], v79, off offset:80
.LBB0_529:
	s_or_b64 exec, exec, s[2:3]
	v_bfe_u32 v79, v72, 16, 1
	v_lshl_add_u64 v[68:69], v[68:69], 1, v[64:65]
	v_add3_u32 v72, v72, v79, s33
	ds_write_b16_d16_hi v84, v72 offset:64
	v_bfe_u32 v72, v76, 16, 1
	s_waitcnt lgkmcnt(0)
	v_add_co_u32_e32 v80, vcc, 0x10000, v68
	v_add3_u32 v72, v76, v72, s33
	s_nop 0
	v_addc_co_u32_e32 v81, vcc, 0, v69, vcc
	ds_write_b16_d16_hi v84, v72 offset:576
	v_bfe_u32 v72, v67, 16, 1
	v_add_co_u32_e32 v80, vcc, 0x4000, v68
	v_add3_u32 v67, v67, v72, s33
	s_nop 0
	v_addc_co_u32_e32 v81, vcc, 0, v69, vcc
	ds_write_b16_d16_hi v84, v67 offset:192
	v_bfe_u32 v67, v75, 16, 1
	v_add_co_u32_e32 v80, vcc, 0x14000, v68
	v_add3_u32 v67, v75, v67, s33
	s_nop 0
	v_addc_co_u32_e32 v81, vcc, 0, v69, vcc
	ds_write_b16_d16_hi v84, v67 offset:704
	v_bfe_u32 v67, v74, 16, 1
	v_add3_u32 v67, v74, v67, s33
	v_add_co_u32_e32 v74, vcc, 0x8000, v68
	v_pk_mul_f32 v[82:83], v[32:33], v[32:33]
	s_nop 0
	v_addc_co_u32_e32 v75, vcc, 0, v69, vcc
	ds_write_b16_d16_hi v84, v67 offset:320
	v_bfe_u32 v67, v78, 16, 1
	v_add_co_u32_e32 v74, vcc, 0x18000, v68
	v_add3_u32 v67, v78, v67, s33
	s_nop 0
	v_addc_co_u32_e32 v75, vcc, 0, v69, vcc
	ds_write_b16_d16_hi v84, v67 offset:832
	v_bfe_u32 v67, v73, 16, 1
	v_add_co_u32_e32 v72, vcc, 0xc000, v68
	v_add3_u32 v67, v73, v67, s33
	s_nop 0
	v_addc_co_u32_e32 v73, vcc, 0, v69, vcc
	ds_write_b16_d16_hi v84, v67 offset:448
	v_and_b32_e32 v73, 0x7fffffff, v37
	v_and_b32_e32 v72, 0x7fffffff, v36
	v_pk_fma_f32 v[72:73], v[72:73], s[90:91], 1.0 op_sel_hi:[1,0,0]
	v_bfe_u32 v67, v77, 16, 1
	v_rcp_f32_e32 v72, v72
	v_rcp_f32_e32 v73, v73
	v_add3_u32 v67, v77, v67, s33
	v_mov_b64_e32 v[78:79], s[16:17]
	v_pk_mul_f32 v[76:77], v[36:37], v[36:37]
	v_pk_fma_f32 v[74:75], v[72:73], s[92:93], v[78:79] op_sel_hi:[1,0,0]
	v_pk_mul_f32 v[76:77], v[76:77], s[66:67] op_sel_hi:[1,0]
	v_pk_fma_f32 v[74:75], v[72:73], v[74:75], s[96:97] op_sel_hi:[1,1,0]
	v_exp_f32_e32 v76, v76
	v_exp_f32_e32 v77, v77
	v_pk_fma_f32 v[74:75], v[72:73], v[74:75], s[12:13] op_sel_hi:[1,1,0]
	v_add_co_u32_e32 v68, vcc, 0x1c000, v68
	v_pk_fma_f32 v[74:75], v[72:73], v[74:75], s[14:15] op_sel_hi:[1,1,0]
	s_nop 0
	v_addc_co_u32_e32 v69, vcc, 0, v69, vcc
	v_pk_mul_f32 v[72:73], v[72:73], v[74:75]
	v_cmp_gt_f32_e32 vcc, 0, v36
	v_pk_mul_f32 v[72:73], v[76:77], v[72:73]
	ds_write_b16_d16_hi v84, v67 offset:960
	v_pk_mul_f32 v[76:77], v[36:37], v[72:73]
	v_pk_fma_f32 v[72:73], v[36:37], v[72:73], v[36:37] neg_lo:[1,0,0] neg_hi:[1,0,0]
	v_pk_mul_f32 v[74:75], v[38:39], v[38:39]
	v_cndmask_b32_e32 v72, v72, v76, vcc
	v_cmp_gt_f32_e32 vcc, 0, v37
	v_and_b32_e32 v76, 0x7fffffff, v38
	v_pk_mul_f32 v[74:75], v[74:75], s[66:67] op_sel_hi:[1,0]
	v_cndmask_b32_e32 v67, v73, v77, vcc
	v_and_b32_e32 v77, 0x7fffffff, v39
	v_pk_fma_f32 v[76:77], v[76:77], s[90:91], 1.0 op_sel_hi:[1,0,0]
	v_exp_f32_e32 v74, v74
	v_rcp_f32_e32 v76, v76
	v_rcp_f32_e32 v77, v77
	v_exp_f32_e32 v75, v75
	v_cmp_gt_f32_e32 vcc, 0, v38
	v_pk_mul_f32 v[82:83], v[82:83], s[66:67] op_sel_hi:[1,0]
	v_pk_fma_f32 v[80:81], v[76:77], s[92:93], v[78:79] op_sel_hi:[1,0,0]
	v_exp_f32_e32 v82, v82
	v_pk_fma_f32 v[80:81], v[76:77], v[80:81], s[96:97] op_sel_hi:[1,1,0]
	v_exp_f32_e32 v83, v83
	v_pk_fma_f32 v[80:81], v[76:77], v[80:81], s[12:13] op_sel_hi:[1,1,0]
	v_mul_f32_e32 v69, v67, v67
	v_pk_fma_f32 v[80:81], v[76:77], v[80:81], s[14:15] op_sel_hi:[1,1,0]
	v_fmac_f32_e32 v69, v72, v72
	v_pk_mul_f32 v[76:77], v[76:77], v[80:81]
	v_or_b32_e32 v68, 48, v66
	v_pk_mul_f32 v[74:75], v[74:75], v[76:77]
	s_nop 0
	v_pk_mul_f32 v[76:77], v[38:39], v[74:75]
	v_pk_fma_f32 v[74:75], v[38:39], v[74:75], v[38:39] neg_lo:[1,0,0] neg_hi:[1,0,0]
	s_nop 0
	v_cndmask_b32_e32 v74, v74, v76, vcc
	v_cmp_gt_f32_e32 vcc, 0, v39
	v_and_b32_e32 v76, 0x7fffffff, v32
	s_nop 0
	v_cndmask_b32_e32 v73, v75, v77, vcc
	v_and_b32_e32 v77, 0x7fffffff, v33
	v_pk_fma_f32 v[76:77], v[76:77], s[90:91], 1.0 op_sel_hi:[1,0,0]
	v_cmp_gt_f32_e32 vcc, 0, v32
	v_rcp_f32_e32 v76, v76
	v_rcp_f32_e32 v77, v77
	s_nop 0
	v_pk_fma_f32 v[80:81], v[76:77], s[92:93], v[78:79] op_sel_hi:[1,0,0]
	s_nop 0
	v_pk_fma_f32 v[80:81], v[76:77], v[80:81], s[96:97] op_sel_hi:[1,1,0]
	s_nop 0
	v_pk_fma_f32 v[80:81], v[76:77], v[80:81], s[12:13] op_sel_hi:[1,1,0]
	s_nop 0
	v_pk_fma_f32 v[80:81], v[76:77], v[80:81], s[14:15] op_sel_hi:[1,1,0]
	s_nop 0
	v_pk_mul_f32 v[76:77], v[76:77], v[80:81]
	v_pk_mul_f32 v[80:81], v[34:35], v[34:35]
	v_pk_mul_f32 v[76:77], v[82:83], v[76:77]
	v_pk_mul_f32 v[80:81], v[80:81], s[66:67] op_sel_hi:[1,0]
	v_pk_mul_f32 v[82:83], v[32:33], v[76:77]
	v_pk_fma_f32 v[76:77], v[32:33], v[76:77], v[32:33] neg_lo:[1,0,0] neg_hi:[1,0,0]
	v_exp_f32_e32 v80, v80
	v_cndmask_b32_e32 v76, v76, v82, vcc
	v_cmp_gt_f32_e32 vcc, 0, v33
	v_and_b32_e32 v82, 0x7fffffff, v34
	v_exp_f32_e32 v81, v81
	v_cndmask_b32_e32 v75, v77, v83, vcc
	v_and_b32_e32 v83, 0x7fffffff, v35
	v_pk_fma_f32 v[82:83], v[82:83], s[90:91], 1.0 op_sel_hi:[1,0,0]
	v_cmp_gt_f32_e32 vcc, 0, v34
	v_rcp_f32_e32 v82, v82
	v_rcp_f32_e32 v83, v83
	s_nop 0
	v_pk_fma_f32 v[78:79], v[82:83], s[92:93], v[78:79] op_sel_hi:[1,0,0]
	s_nop 0
	v_pk_fma_f32 v[78:79], v[82:83], v[78:79], s[96:97] op_sel_hi:[1,1,0]
	s_nop 0
	v_pk_fma_f32 v[78:79], v[82:83], v[78:79], s[12:13] op_sel_hi:[1,1,0]
	s_nop 0
	v_pk_fma_f32 v[78:79], v[82:83], v[78:79], s[14:15] op_sel_hi:[1,1,0]
	s_nop 0
	v_pk_mul_f32 v[78:79], v[82:83], v[78:79]
	s_nop 0
	v_pk_mul_f32 v[78:79], v[80:81], v[78:79]
	s_nop 0
	v_pk_mul_f32 v[80:81], v[34:35], v[78:79]
	v_pk_fma_f32 v[78:79], v[34:35], v[78:79], v[34:35] neg_lo:[1,0,0] neg_hi:[1,0,0]
	s_nop 0
	v_cndmask_b32_e32 v78, v78, v80, vcc
	v_cmp_gt_f32_e32 vcc, 0, v35
	s_nop 1
	v_cndmask_b32_e32 v77, v79, v81, vcc
	v_mul_f32_e32 v79, v73, v73
	v_fmac_f32_e32 v79, v74, v74
	v_add_f32_e32 v69, v69, v79
	v_mul_f32_e32 v79, v75, v75
	v_mul_f32_e32 v80, v77, v77
	v_fmac_f32_e32 v79, v76, v76
	v_fmac_f32_e32 v80, v78, v78
	v_add_f32_e32 v79, v79, v80
	v_add_f32_e32 v69, v69, v79
	ds_bpermute_b32 v79, v70, v69
	s_waitcnt lgkmcnt(0)
	v_add_f32_e32 v79, v69, v79
	ds_bpermute_b32 v80, v71, v79
	v_ashrrev_i32_e32 v69, 31, v68
	s_and_saveexec_b64 s[2:3], s[4:5]
	s_xor_b64 s[2:3], exec, s[2:3]
	s_andn2_saveexec_b64 s[2:3], s[2:3]
	s_cbranch_execz .LBB0_533
	s_waitcnt lgkmcnt(0)
	v_add_f32_e32 v79, v79, v80
	v_mov_b64_e32 v[80:81], s[8:9]
	v_mad_i64_i32 v[80:81], s[34:35], v68, s18, v[80:81]
	s_lshl_b32 s80, s15, 2
	v_lshl_add_u64 v[80:81], v[80:81], 0, s[80:81]
	global_store_dword v[80:81], v79, off offset:80
.LBB0_533:
	s_or_b64 exec, exec, s[2:3]
	v_bfe_u32 v79, v72, 16, 1
	v_lshl_add_u64 v[68:69], v[68:69], 1, v[64:65]
	v_add3_u32 v72, v72, v79, s33
	ds_write_b16_d16_hi v84, v72 offset:96
	v_bfe_u32 v72, v76, 16, 1
	s_waitcnt lgkmcnt(0)
	v_add_co_u32_e32 v80, vcc, 0x10000, v68
	v_add3_u32 v72, v76, v72, s33
	s_nop 0
	v_addc_co_u32_e32 v81, vcc, 0, v69, vcc
	ds_write_b16_d16_hi v84, v72 offset:608
	v_bfe_u32 v72, v67, 16, 1
	v_add_co_u32_e32 v80, vcc, 0x4000, v68
	v_add3_u32 v67, v67, v72, s33
	s_nop 0
	v_addc_co_u32_e32 v81, vcc, 0, v69, vcc
	ds_write_b16_d16_hi v84, v67 offset:224
	v_bfe_u32 v67, v75, 16, 1
	v_add_co_u32_e32 v80, vcc, 0x14000, v68
	v_add3_u32 v67, v75, v67, s33
	s_nop 0
	v_addc_co_u32_e32 v81, vcc, 0, v69, vcc
	ds_write_b16_d16_hi v84, v67 offset:736
	v_bfe_u32 v67, v74, 16, 1
	v_add3_u32 v67, v74, v67, s33
	v_add_co_u32_e32 v74, vcc, 0x8000, v68
	v_pk_mul_f32 v[82:83], v[24:25], v[24:25]
	s_nop 0
	v_addc_co_u32_e32 v75, vcc, 0, v69, vcc
	ds_write_b16_d16_hi v84, v67 offset:352
	v_bfe_u32 v67, v78, 16, 1
	v_add_co_u32_e32 v74, vcc, 0x18000, v68
	v_add3_u32 v67, v78, v67, s33
	s_nop 0
	v_addc_co_u32_e32 v75, vcc, 0, v69, vcc
	ds_write_b16_d16_hi v84, v67 offset:864
	v_bfe_u32 v67, v73, 16, 1
	v_add_co_u32_e32 v72, vcc, 0xc000, v68
	v_add3_u32 v67, v73, v67, s33
	s_nop 0
	v_addc_co_u32_e32 v73, vcc, 0, v69, vcc
	ds_write_b16_d16_hi v84, v67 offset:480
	v_and_b32_e32 v73, 0x7fffffff, v29
	v_and_b32_e32 v72, 0x7fffffff, v28
	v_pk_fma_f32 v[72:73], v[72:73], s[90:91], 1.0 op_sel_hi:[1,0,0]
	v_bfe_u32 v67, v77, 16, 1
	v_rcp_f32_e32 v72, v72
	v_rcp_f32_e32 v73, v73
	v_add3_u32 v67, v77, v67, s33
	v_mov_b64_e32 v[78:79], s[16:17]
	v_pk_mul_f32 v[76:77], v[28:29], v[28:29]
	v_pk_fma_f32 v[74:75], v[72:73], s[92:93], v[78:79] op_sel_hi:[1,0,0]
	v_pk_mul_f32 v[76:77], v[76:77], s[66:67] op_sel_hi:[1,0]
	v_pk_fma_f32 v[74:75], v[72:73], v[74:75], s[96:97] op_sel_hi:[1,1,0]
	v_exp_f32_e32 v76, v76
	v_exp_f32_e32 v77, v77
	v_pk_fma_f32 v[74:75], v[72:73], v[74:75], s[12:13] op_sel_hi:[1,1,0]
	v_add_co_u32_e32 v68, vcc, 0x1c000, v68
	v_pk_fma_f32 v[74:75], v[72:73], v[74:75], s[14:15] op_sel_hi:[1,1,0]
	s_nop 0
	v_addc_co_u32_e32 v69, vcc, 0, v69, vcc
	v_pk_mul_f32 v[72:73], v[72:73], v[74:75]
	v_cmp_gt_f32_e32 vcc, 0, v28
	v_pk_mul_f32 v[72:73], v[76:77], v[72:73]
	ds_write_b16_d16_hi v84, v67 offset:992
	v_pk_mul_f32 v[76:77], v[28:29], v[72:73]
	v_pk_fma_f32 v[72:73], v[28:29], v[72:73], v[28:29] neg_lo:[1,0,0] neg_hi:[1,0,0]
	v_pk_mul_f32 v[74:75], v[30:31], v[30:31]
	v_cndmask_b32_e32 v72, v72, v76, vcc
	v_cmp_gt_f32_e32 vcc, 0, v29
	v_and_b32_e32 v76, 0x7fffffff, v30
	v_pk_mul_f32 v[74:75], v[74:75], s[66:67] op_sel_hi:[1,0]
	v_cndmask_b32_e32 v67, v73, v77, vcc
	v_and_b32_e32 v77, 0x7fffffff, v31
	v_pk_fma_f32 v[76:77], v[76:77], s[90:91], 1.0 op_sel_hi:[1,0,0]
	v_exp_f32_e32 v74, v74
	v_rcp_f32_e32 v76, v76
	v_rcp_f32_e32 v77, v77
	v_exp_f32_e32 v75, v75
	v_cmp_gt_f32_e32 vcc, 0, v30
	v_pk_mul_f32 v[82:83], v[82:83], s[66:67] op_sel_hi:[1,0]
	v_pk_fma_f32 v[80:81], v[76:77], s[92:93], v[78:79] op_sel_hi:[1,0,0]
	v_exp_f32_e32 v82, v82
	v_pk_fma_f32 v[80:81], v[76:77], v[80:81], s[96:97] op_sel_hi:[1,1,0]
	v_exp_f32_e32 v83, v83
	v_pk_fma_f32 v[80:81], v[76:77], v[80:81], s[12:13] op_sel_hi:[1,1,0]
	v_mul_f32_e32 v69, v67, v67
	v_pk_fma_f32 v[80:81], v[76:77], v[80:81], s[14:15] op_sel_hi:[1,1,0]
	v_fmac_f32_e32 v69, v72, v72
	v_pk_mul_f32 v[76:77], v[76:77], v[80:81]
	v_add_u32_e32 v68, 0x80, v66
	v_pk_mul_f32 v[74:75], v[74:75], v[76:77]
	s_nop 0
	v_pk_mul_f32 v[76:77], v[30:31], v[74:75]
	v_pk_fma_f32 v[74:75], v[30:31], v[74:75], v[30:31] neg_lo:[1,0,0] neg_hi:[1,0,0]
	s_nop 0
	v_cndmask_b32_e32 v74, v74, v76, vcc
	v_cmp_gt_f32_e32 vcc, 0, v31
	v_and_b32_e32 v76, 0x7fffffff, v24
	s_nop 0
	v_cndmask_b32_e32 v73, v75, v77, vcc
	v_and_b32_e32 v77, 0x7fffffff, v25
	v_pk_fma_f32 v[76:77], v[76:77], s[90:91], 1.0 op_sel_hi:[1,0,0]
	v_cmp_gt_f32_e32 vcc, 0, v24
	v_rcp_f32_e32 v76, v76
	v_rcp_f32_e32 v77, v77
	s_nop 0
	v_pk_fma_f32 v[80:81], v[76:77], s[92:93], v[78:79] op_sel_hi:[1,0,0]
	s_nop 0
	v_pk_fma_f32 v[80:81], v[76:77], v[80:81], s[96:97] op_sel_hi:[1,1,0]
	s_nop 0
	v_pk_fma_f32 v[80:81], v[76:77], v[80:81], s[12:13] op_sel_hi:[1,1,0]
	s_nop 0
	v_pk_fma_f32 v[80:81], v[76:77], v[80:81], s[14:15] op_sel_hi:[1,1,0]
	s_nop 0
	v_pk_mul_f32 v[76:77], v[76:77], v[80:81]
	v_pk_mul_f32 v[80:81], v[26:27], v[26:27]
	v_pk_mul_f32 v[76:77], v[82:83], v[76:77]
	v_pk_mul_f32 v[80:81], v[80:81], s[66:67] op_sel_hi:[1,0]
	v_pk_mul_f32 v[82:83], v[24:25], v[76:77]
	v_pk_fma_f32 v[76:77], v[24:25], v[76:77], v[24:25] neg_lo:[1,0,0] neg_hi:[1,0,0]
	v_exp_f32_e32 v80, v80
	v_cndmask_b32_e32 v76, v76, v82, vcc
	v_cmp_gt_f32_e32 vcc, 0, v25
	v_and_b32_e32 v82, 0x7fffffff, v26
	v_exp_f32_e32 v81, v81
	v_cndmask_b32_e32 v75, v77, v83, vcc
	v_and_b32_e32 v83, 0x7fffffff, v27
	v_pk_fma_f32 v[82:83], v[82:83], s[90:91], 1.0 op_sel_hi:[1,0,0]
	v_cmp_gt_f32_e32 vcc, 0, v26
	v_rcp_f32_e32 v82, v82
	v_rcp_f32_e32 v83, v83
	s_nop 0
	v_pk_fma_f32 v[78:79], v[82:83], s[92:93], v[78:79] op_sel_hi:[1,0,0]
	s_nop 0
	v_pk_fma_f32 v[78:79], v[82:83], v[78:79], s[96:97] op_sel_hi:[1,1,0]
	s_nop 0
	v_pk_fma_f32 v[78:79], v[82:83], v[78:79], s[12:13] op_sel_hi:[1,1,0]
	s_nop 0
	v_pk_fma_f32 v[78:79], v[82:83], v[78:79], s[14:15] op_sel_hi:[1,1,0]
	s_nop 0
	v_pk_mul_f32 v[78:79], v[82:83], v[78:79]
	s_nop 0
	v_pk_mul_f32 v[78:79], v[80:81], v[78:79]
	s_nop 0
	v_pk_mul_f32 v[80:81], v[26:27], v[78:79]
	v_pk_fma_f32 v[78:79], v[26:27], v[78:79], v[26:27] neg_lo:[1,0,0] neg_hi:[1,0,0]
	s_nop 0
	v_cndmask_b32_e32 v78, v78, v80, vcc
	v_cmp_gt_f32_e32 vcc, 0, v27
	s_nop 1
	v_cndmask_b32_e32 v77, v79, v81, vcc
	v_mul_f32_e32 v79, v73, v73
	v_fmac_f32_e32 v79, v74, v74
	v_add_f32_e32 v69, v69, v79
	v_mul_f32_e32 v79, v75, v75
	v_mul_f32_e32 v80, v77, v77
	v_fmac_f32_e32 v79, v76, v76
	v_fmac_f32_e32 v80, v78, v78
	v_add_f32_e32 v79, v79, v80
	v_add_f32_e32 v69, v69, v79
	ds_bpermute_b32 v79, v70, v69
	s_waitcnt lgkmcnt(0)
	v_add_f32_e32 v79, v69, v79
	ds_bpermute_b32 v80, v71, v79
	v_ashrrev_i32_e32 v69, 31, v68
	s_and_saveexec_b64 s[2:3], s[4:5]
	s_xor_b64 s[2:3], exec, s[2:3]
	s_andn2_saveexec_b64 s[2:3], s[2:3]
	s_cbranch_execz .LBB0_537
	s_waitcnt lgkmcnt(0)
	v_add_f32_e32 v79, v79, v80
	v_mov_b64_e32 v[80:81], s[8:9]
	v_mad_i64_i32 v[80:81], s[34:35], v68, s18, v[80:81]
	s_lshl_b32 s80, s15, 2
	v_lshl_add_u64 v[80:81], v[80:81], 0, s[80:81]
	global_store_dword v[80:81], v79, off offset:80
.LBB0_537:
	s_or_b64 exec, exec, s[2:3]
	v_bfe_u32 v79, v72, 16, 1
	v_lshl_add_u64 v[68:69], v[68:69], 1, v[64:65]
	v_add3_u32 v72, v72, v79, s33
	ds_write_b16_d16_hi v84, v72 offset:32768
	v_bfe_u32 v72, v76, 16, 1
	s_waitcnt lgkmcnt(0)
	v_add_co_u32_e32 v80, vcc, 0x10000, v68
	v_add3_u32 v72, v76, v72, s33
	s_nop 0
	v_addc_co_u32_e32 v81, vcc, 0, v69, vcc
	ds_write_b16_d16_hi v84, v72 offset:33280
	v_bfe_u32 v72, v67, 16, 1
	v_add_co_u32_e32 v80, vcc, 0x4000, v68
	v_add3_u32 v67, v67, v72, s33
	s_nop 0
	v_addc_co_u32_e32 v81, vcc, 0, v69, vcc
	ds_write_b16_d16_hi v84, v67 offset:32896
	v_bfe_u32 v67, v75, 16, 1
	v_add_co_u32_e32 v80, vcc, 0x14000, v68
	v_add3_u32 v67, v75, v67, s33
	s_nop 0
	v_addc_co_u32_e32 v81, vcc, 0, v69, vcc
	ds_write_b16_d16_hi v84, v67 offset:33408
	v_bfe_u32 v67, v74, 16, 1
	v_add3_u32 v67, v74, v67, s33
	v_add_co_u32_e32 v74, vcc, 0x8000, v68
	v_pk_mul_f32 v[82:83], v[16:17], v[16:17]
	s_nop 0
	v_addc_co_u32_e32 v75, vcc, 0, v69, vcc
	ds_write_b16_d16_hi v84, v67 offset:33024
	v_bfe_u32 v67, v78, 16, 1
	v_add_co_u32_e32 v74, vcc, 0x18000, v68
	v_add3_u32 v67, v78, v67, s33
	s_nop 0
	v_addc_co_u32_e32 v75, vcc, 0, v69, vcc
	ds_write_b16_d16_hi v84, v67 offset:33536
	v_bfe_u32 v67, v73, 16, 1
	v_add_co_u32_e32 v72, vcc, 0xc000, v68
	v_add3_u32 v67, v73, v67, s33
	s_nop 0
	v_addc_co_u32_e32 v73, vcc, 0, v69, vcc
	ds_write_b16_d16_hi v84, v67 offset:33152
	v_and_b32_e32 v73, 0x7fffffff, v21
	v_and_b32_e32 v72, 0x7fffffff, v20
	v_pk_fma_f32 v[72:73], v[72:73], s[90:91], 1.0 op_sel_hi:[1,0,0]
	v_bfe_u32 v67, v77, 16, 1
	v_rcp_f32_e32 v72, v72
	v_rcp_f32_e32 v73, v73
	v_add3_u32 v67, v77, v67, s33
	v_mov_b64_e32 v[78:79], s[16:17]
	v_pk_mul_f32 v[76:77], v[20:21], v[20:21]
	v_pk_fma_f32 v[74:75], v[72:73], s[92:93], v[78:79] op_sel_hi:[1,0,0]
	v_pk_mul_f32 v[76:77], v[76:77], s[66:67] op_sel_hi:[1,0]
	v_pk_fma_f32 v[74:75], v[72:73], v[74:75], s[96:97] op_sel_hi:[1,1,0]
	v_exp_f32_e32 v76, v76
	v_exp_f32_e32 v77, v77
	v_pk_fma_f32 v[74:75], v[72:73], v[74:75], s[12:13] op_sel_hi:[1,1,0]
	v_add_co_u32_e32 v68, vcc, 0x1c000, v68
	v_pk_fma_f32 v[74:75], v[72:73], v[74:75], s[14:15] op_sel_hi:[1,1,0]
	s_nop 0
	v_addc_co_u32_e32 v69, vcc, 0, v69, vcc
	v_pk_mul_f32 v[72:73], v[72:73], v[74:75]
	v_cmp_gt_f32_e32 vcc, 0, v20
	v_pk_mul_f32 v[72:73], v[76:77], v[72:73]
	ds_write_b16_d16_hi v84, v67 offset:33664
	v_pk_mul_f32 v[76:77], v[20:21], v[72:73]
	v_pk_fma_f32 v[72:73], v[20:21], v[72:73], v[20:21] neg_lo:[1,0,0] neg_hi:[1,0,0]
	v_pk_mul_f32 v[74:75], v[22:23], v[22:23]
	v_cndmask_b32_e32 v72, v72, v76, vcc
	v_cmp_gt_f32_e32 vcc, 0, v21
	v_and_b32_e32 v76, 0x7fffffff, v22
	v_pk_mul_f32 v[74:75], v[74:75], s[66:67] op_sel_hi:[1,0]
	v_cndmask_b32_e32 v67, v73, v77, vcc
	v_and_b32_e32 v77, 0x7fffffff, v23
	v_pk_fma_f32 v[76:77], v[76:77], s[90:91], 1.0 op_sel_hi:[1,0,0]
	v_exp_f32_e32 v74, v74
	v_rcp_f32_e32 v76, v76
	v_rcp_f32_e32 v77, v77
	v_exp_f32_e32 v75, v75
	v_cmp_gt_f32_e32 vcc, 0, v22
	v_pk_mul_f32 v[82:83], v[82:83], s[66:67] op_sel_hi:[1,0]
	v_pk_fma_f32 v[80:81], v[76:77], s[92:93], v[78:79] op_sel_hi:[1,0,0]
	v_exp_f32_e32 v82, v82
	v_pk_fma_f32 v[80:81], v[76:77], v[80:81], s[96:97] op_sel_hi:[1,1,0]
	v_exp_f32_e32 v83, v83
	v_pk_fma_f32 v[80:81], v[76:77], v[80:81], s[12:13] op_sel_hi:[1,1,0]
	v_mul_f32_e32 v69, v67, v67
	v_pk_fma_f32 v[80:81], v[76:77], v[80:81], s[14:15] op_sel_hi:[1,1,0]
	v_fmac_f32_e32 v69, v72, v72
	v_pk_mul_f32 v[76:77], v[76:77], v[80:81]
	v_add_u32_e32 v68, 0x90, v66
	v_pk_mul_f32 v[74:75], v[74:75], v[76:77]
	s_nop 0
	v_pk_mul_f32 v[76:77], v[22:23], v[74:75]
	v_pk_fma_f32 v[74:75], v[22:23], v[74:75], v[22:23] neg_lo:[1,0,0] neg_hi:[1,0,0]
	s_nop 0
	v_cndmask_b32_e32 v74, v74, v76, vcc
	v_cmp_gt_f32_e32 vcc, 0, v23
	v_and_b32_e32 v76, 0x7fffffff, v16
	s_nop 0
	v_cndmask_b32_e32 v73, v75, v77, vcc
	v_and_b32_e32 v77, 0x7fffffff, v17
	v_pk_fma_f32 v[76:77], v[76:77], s[90:91], 1.0 op_sel_hi:[1,0,0]
	v_cmp_gt_f32_e32 vcc, 0, v16
	v_rcp_f32_e32 v76, v76
	v_rcp_f32_e32 v77, v77
	s_nop 0
	v_pk_fma_f32 v[80:81], v[76:77], s[92:93], v[78:79] op_sel_hi:[1,0,0]
	s_nop 0
	v_pk_fma_f32 v[80:81], v[76:77], v[80:81], s[96:97] op_sel_hi:[1,1,0]
	s_nop 0
	v_pk_fma_f32 v[80:81], v[76:77], v[80:81], s[12:13] op_sel_hi:[1,1,0]
	s_nop 0
	v_pk_fma_f32 v[80:81], v[76:77], v[80:81], s[14:15] op_sel_hi:[1,1,0]
	s_nop 0
	v_pk_mul_f32 v[76:77], v[76:77], v[80:81]
	v_pk_mul_f32 v[80:81], v[18:19], v[18:19]
	v_pk_mul_f32 v[76:77], v[82:83], v[76:77]
	v_pk_mul_f32 v[80:81], v[80:81], s[66:67] op_sel_hi:[1,0]
	v_pk_mul_f32 v[82:83], v[16:17], v[76:77]
	v_pk_fma_f32 v[76:77], v[16:17], v[76:77], v[16:17] neg_lo:[1,0,0] neg_hi:[1,0,0]
	v_exp_f32_e32 v80, v80
	v_cndmask_b32_e32 v76, v76, v82, vcc
	v_cmp_gt_f32_e32 vcc, 0, v17
	v_and_b32_e32 v82, 0x7fffffff, v18
	v_exp_f32_e32 v81, v81
	v_cndmask_b32_e32 v75, v77, v83, vcc
	v_and_b32_e32 v83, 0x7fffffff, v19
	v_pk_fma_f32 v[82:83], v[82:83], s[90:91], 1.0 op_sel_hi:[1,0,0]
	v_cmp_gt_f32_e32 vcc, 0, v18
	v_rcp_f32_e32 v82, v82
	v_rcp_f32_e32 v83, v83
	s_nop 0
	v_pk_fma_f32 v[78:79], v[82:83], s[92:93], v[78:79] op_sel_hi:[1,0,0]
	s_nop 0
	v_pk_fma_f32 v[78:79], v[82:83], v[78:79], s[96:97] op_sel_hi:[1,1,0]
	s_nop 0
	v_pk_fma_f32 v[78:79], v[82:83], v[78:79], s[12:13] op_sel_hi:[1,1,0]
	s_nop 0
	v_pk_fma_f32 v[78:79], v[82:83], v[78:79], s[14:15] op_sel_hi:[1,1,0]
	s_nop 0
	v_pk_mul_f32 v[78:79], v[82:83], v[78:79]
	s_nop 0
	v_pk_mul_f32 v[78:79], v[80:81], v[78:79]
	s_nop 0
	v_pk_mul_f32 v[80:81], v[18:19], v[78:79]
	v_pk_fma_f32 v[78:79], v[18:19], v[78:79], v[18:19] neg_lo:[1,0,0] neg_hi:[1,0,0]
	s_nop 0
	v_cndmask_b32_e32 v78, v78, v80, vcc
	v_cmp_gt_f32_e32 vcc, 0, v19
	s_nop 1
	v_cndmask_b32_e32 v77, v79, v81, vcc
	v_mul_f32_e32 v79, v73, v73
	v_fmac_f32_e32 v79, v74, v74
	v_add_f32_e32 v69, v69, v79
	v_mul_f32_e32 v79, v75, v75
	v_mul_f32_e32 v80, v77, v77
	v_fmac_f32_e32 v79, v76, v76
	v_fmac_f32_e32 v80, v78, v78
	v_add_f32_e32 v79, v79, v80
	v_add_f32_e32 v69, v69, v79
	ds_bpermute_b32 v79, v70, v69
	s_waitcnt lgkmcnt(0)
	v_add_f32_e32 v79, v69, v79
	ds_bpermute_b32 v80, v71, v79
	v_ashrrev_i32_e32 v69, 31, v68
	s_and_saveexec_b64 s[2:3], s[4:5]
	s_xor_b64 s[2:3], exec, s[2:3]
	s_andn2_saveexec_b64 s[2:3], s[2:3]
	s_cbranch_execz .LBB0_541
	s_waitcnt lgkmcnt(0)
	v_add_f32_e32 v79, v79, v80
	v_mov_b64_e32 v[80:81], s[8:9]
	v_mad_i64_i32 v[80:81], s[34:35], v68, s18, v[80:81]
	s_lshl_b32 s80, s15, 2
	v_lshl_add_u64 v[80:81], v[80:81], 0, s[80:81]
	global_store_dword v[80:81], v79, off offset:80
.LBB0_541:
	s_or_b64 exec, exec, s[2:3]
	v_bfe_u32 v79, v72, 16, 1
	v_lshl_add_u64 v[68:69], v[68:69], 1, v[64:65]
	v_add3_u32 v72, v72, v79, s33
	ds_write_b16_d16_hi v84, v72 offset:32800
	v_bfe_u32 v72, v76, 16, 1
	s_waitcnt lgkmcnt(0)
	v_add_co_u32_e32 v80, vcc, 0x10000, v68
	v_add3_u32 v72, v76, v72, s33
	s_nop 0
	v_addc_co_u32_e32 v81, vcc, 0, v69, vcc
	ds_write_b16_d16_hi v84, v72 offset:33312
	v_bfe_u32 v72, v67, 16, 1
	v_add_co_u32_e32 v80, vcc, 0x4000, v68
	v_add3_u32 v67, v67, v72, s33
	s_nop 0
	v_addc_co_u32_e32 v81, vcc, 0, v69, vcc
	ds_write_b16_d16_hi v84, v67 offset:32928
	v_bfe_u32 v67, v75, 16, 1
	v_add_co_u32_e32 v80, vcc, 0x14000, v68
	v_add3_u32 v67, v75, v67, s33
	s_nop 0
	v_addc_co_u32_e32 v81, vcc, 0, v69, vcc
	ds_write_b16_d16_hi v84, v67 offset:33440
	v_bfe_u32 v67, v74, 16, 1
	v_add3_u32 v67, v74, v67, s33
	v_add_co_u32_e32 v74, vcc, 0x8000, v68
	v_pk_mul_f32 v[82:83], v[8:9], v[8:9]
	s_nop 0
	v_addc_co_u32_e32 v75, vcc, 0, v69, vcc
	ds_write_b16_d16_hi v84, v67 offset:33056
	v_bfe_u32 v67, v78, 16, 1
	v_add_co_u32_e32 v74, vcc, 0x18000, v68
	v_add3_u32 v67, v78, v67, s33
	s_nop 0
	v_addc_co_u32_e32 v75, vcc, 0, v69, vcc
	ds_write_b16_d16_hi v84, v67 offset:33568
	v_bfe_u32 v67, v73, 16, 1
	v_add_co_u32_e32 v72, vcc, 0xc000, v68
	v_add3_u32 v67, v73, v67, s33
	s_nop 0
	v_addc_co_u32_e32 v73, vcc, 0, v69, vcc
	ds_write_b16_d16_hi v84, v67 offset:33184
	v_and_b32_e32 v73, 0x7fffffff, v13
	v_and_b32_e32 v72, 0x7fffffff, v12
	v_pk_fma_f32 v[72:73], v[72:73], s[90:91], 1.0 op_sel_hi:[1,0,0]
	v_bfe_u32 v67, v77, 16, 1
	v_rcp_f32_e32 v72, v72
	v_rcp_f32_e32 v73, v73
	v_add3_u32 v67, v77, v67, s33
	v_mov_b64_e32 v[78:79], s[16:17]
	v_pk_mul_f32 v[76:77], v[12:13], v[12:13]
	v_pk_fma_f32 v[74:75], v[72:73], s[92:93], v[78:79] op_sel_hi:[1,0,0]
	v_pk_mul_f32 v[76:77], v[76:77], s[66:67] op_sel_hi:[1,0]
	v_pk_fma_f32 v[74:75], v[72:73], v[74:75], s[96:97] op_sel_hi:[1,1,0]
	v_exp_f32_e32 v76, v76
	v_exp_f32_e32 v77, v77
	v_pk_fma_f32 v[74:75], v[72:73], v[74:75], s[12:13] op_sel_hi:[1,1,0]
	v_add_co_u32_e32 v68, vcc, 0x1c000, v68
	v_pk_fma_f32 v[74:75], v[72:73], v[74:75], s[14:15] op_sel_hi:[1,1,0]
	s_nop 0
	v_addc_co_u32_e32 v69, vcc, 0, v69, vcc
	v_pk_mul_f32 v[72:73], v[72:73], v[74:75]
	v_cmp_gt_f32_e32 vcc, 0, v12
	v_pk_mul_f32 v[72:73], v[76:77], v[72:73]
	ds_write_b16_d16_hi v84, v67 offset:33696
	v_pk_mul_f32 v[76:77], v[12:13], v[72:73]
	v_pk_fma_f32 v[72:73], v[12:13], v[72:73], v[12:13] neg_lo:[1,0,0] neg_hi:[1,0,0]
	v_pk_mul_f32 v[74:75], v[14:15], v[14:15]
	v_cndmask_b32_e32 v72, v72, v76, vcc
	v_cmp_gt_f32_e32 vcc, 0, v13
	v_and_b32_e32 v76, 0x7fffffff, v14
	v_pk_mul_f32 v[74:75], v[74:75], s[66:67] op_sel_hi:[1,0]
	v_cndmask_b32_e32 v67, v73, v77, vcc
	v_and_b32_e32 v77, 0x7fffffff, v15
	v_pk_fma_f32 v[76:77], v[76:77], s[90:91], 1.0 op_sel_hi:[1,0,0]
	v_exp_f32_e32 v74, v74
	v_rcp_f32_e32 v76, v76
	v_rcp_f32_e32 v77, v77
	v_exp_f32_e32 v75, v75
	v_cmp_gt_f32_e32 vcc, 0, v14
	v_pk_mul_f32 v[82:83], v[82:83], s[66:67] op_sel_hi:[1,0]
	v_pk_fma_f32 v[80:81], v[76:77], s[92:93], v[78:79] op_sel_hi:[1,0,0]
	v_exp_f32_e32 v82, v82
	v_pk_fma_f32 v[80:81], v[76:77], v[80:81], s[96:97] op_sel_hi:[1,1,0]
	v_exp_f32_e32 v83, v83
	v_pk_fma_f32 v[80:81], v[76:77], v[80:81], s[12:13] op_sel_hi:[1,1,0]
	v_mul_f32_e32 v69, v67, v67
	v_pk_fma_f32 v[80:81], v[76:77], v[80:81], s[14:15] op_sel_hi:[1,1,0]
	v_fmac_f32_e32 v69, v72, v72
	v_pk_mul_f32 v[76:77], v[76:77], v[80:81]
	v_add_u32_e32 v68, 0xa0, v66
	v_pk_mul_f32 v[74:75], v[74:75], v[76:77]
	s_nop 0
	v_pk_mul_f32 v[76:77], v[14:15], v[74:75]
	v_pk_fma_f32 v[74:75], v[14:15], v[74:75], v[14:15] neg_lo:[1,0,0] neg_hi:[1,0,0]
	s_nop 0
	v_cndmask_b32_e32 v74, v74, v76, vcc
	v_cmp_gt_f32_e32 vcc, 0, v15
	v_and_b32_e32 v76, 0x7fffffff, v8
	s_nop 0
	v_cndmask_b32_e32 v73, v75, v77, vcc
	v_and_b32_e32 v77, 0x7fffffff, v9
	v_pk_fma_f32 v[76:77], v[76:77], s[90:91], 1.0 op_sel_hi:[1,0,0]
	v_cmp_gt_f32_e32 vcc, 0, v8
	v_rcp_f32_e32 v76, v76
	v_rcp_f32_e32 v77, v77
	s_nop 0
	v_pk_fma_f32 v[80:81], v[76:77], s[92:93], v[78:79] op_sel_hi:[1,0,0]
	s_nop 0
	v_pk_fma_f32 v[80:81], v[76:77], v[80:81], s[96:97] op_sel_hi:[1,1,0]
	s_nop 0
	v_pk_fma_f32 v[80:81], v[76:77], v[80:81], s[12:13] op_sel_hi:[1,1,0]
	s_nop 0
	v_pk_fma_f32 v[80:81], v[76:77], v[80:81], s[14:15] op_sel_hi:[1,1,0]
	s_nop 0
	v_pk_mul_f32 v[76:77], v[76:77], v[80:81]
	v_pk_mul_f32 v[80:81], v[10:11], v[10:11]
	v_pk_mul_f32 v[76:77], v[82:83], v[76:77]
	v_pk_mul_f32 v[80:81], v[80:81], s[66:67] op_sel_hi:[1,0]
	v_pk_mul_f32 v[82:83], v[8:9], v[76:77]
	v_pk_fma_f32 v[76:77], v[8:9], v[76:77], v[8:9] neg_lo:[1,0,0] neg_hi:[1,0,0]
	v_exp_f32_e32 v80, v80
	v_cndmask_b32_e32 v76, v76, v82, vcc
	v_cmp_gt_f32_e32 vcc, 0, v9
	v_and_b32_e32 v82, 0x7fffffff, v10
	v_exp_f32_e32 v81, v81
	v_cndmask_b32_e32 v75, v77, v83, vcc
	v_and_b32_e32 v83, 0x7fffffff, v11
	v_pk_fma_f32 v[82:83], v[82:83], s[90:91], 1.0 op_sel_hi:[1,0,0]
	v_cmp_gt_f32_e32 vcc, 0, v10
	v_rcp_f32_e32 v82, v82
	v_rcp_f32_e32 v83, v83
	s_nop 0
	v_pk_fma_f32 v[78:79], v[82:83], s[92:93], v[78:79] op_sel_hi:[1,0,0]
	s_nop 0
	v_pk_fma_f32 v[78:79], v[82:83], v[78:79], s[96:97] op_sel_hi:[1,1,0]
	s_nop 0
	v_pk_fma_f32 v[78:79], v[82:83], v[78:79], s[12:13] op_sel_hi:[1,1,0]
	s_nop 0
	v_pk_fma_f32 v[78:79], v[82:83], v[78:79], s[14:15] op_sel_hi:[1,1,0]
	s_nop 0
	v_pk_mul_f32 v[78:79], v[82:83], v[78:79]
	s_nop 0
	v_pk_mul_f32 v[78:79], v[80:81], v[78:79]
	s_nop 0
	v_pk_mul_f32 v[80:81], v[10:11], v[78:79]
	v_pk_fma_f32 v[78:79], v[10:11], v[78:79], v[10:11] neg_lo:[1,0,0] neg_hi:[1,0,0]
	s_nop 0
	v_cndmask_b32_e32 v78, v78, v80, vcc
	v_cmp_gt_f32_e32 vcc, 0, v11
	s_nop 1
	v_cndmask_b32_e32 v77, v79, v81, vcc
	v_mul_f32_e32 v79, v73, v73
	v_fmac_f32_e32 v79, v74, v74
	v_add_f32_e32 v69, v69, v79
	v_mul_f32_e32 v79, v75, v75
	v_mul_f32_e32 v80, v77, v77
	v_fmac_f32_e32 v79, v76, v76
	v_fmac_f32_e32 v80, v78, v78
	v_add_f32_e32 v79, v79, v80
	v_add_f32_e32 v69, v69, v79
	ds_bpermute_b32 v79, v70, v69
	s_waitcnt lgkmcnt(0)
	v_add_f32_e32 v79, v69, v79
	ds_bpermute_b32 v80, v71, v79
	v_ashrrev_i32_e32 v69, 31, v68
	s_and_saveexec_b64 s[2:3], s[4:5]
	s_xor_b64 s[2:3], exec, s[2:3]
	s_andn2_saveexec_b64 s[2:3], s[2:3]
	s_cbranch_execz .LBB0_545
	s_waitcnt lgkmcnt(0)
	v_add_f32_e32 v79, v79, v80
	v_mov_b64_e32 v[80:81], s[8:9]
	v_mad_i64_i32 v[80:81], s[34:35], v68, s18, v[80:81]
	s_lshl_b32 s80, s15, 2
	v_lshl_add_u64 v[80:81], v[80:81], 0, s[80:81]
	global_store_dword v[80:81], v79, off offset:80
.LBB0_545:
	s_or_b64 exec, exec, s[2:3]
	v_bfe_u32 v79, v72, 16, 1
	v_lshl_add_u64 v[68:69], v[68:69], 1, v[64:65]
	v_add3_u32 v72, v72, v79, s33
	ds_write_b16_d16_hi v84, v72 offset:32832
	v_bfe_u32 v72, v76, 16, 1
	s_waitcnt lgkmcnt(0)
	v_add_co_u32_e32 v80, vcc, 0x10000, v68
	v_add3_u32 v72, v76, v72, s33
	s_nop 0
	v_addc_co_u32_e32 v81, vcc, 0, v69, vcc
	ds_write_b16_d16_hi v84, v72 offset:33344
	v_bfe_u32 v72, v67, 16, 1
	v_add_co_u32_e32 v80, vcc, 0x4000, v68
	v_add3_u32 v67, v67, v72, s33
	s_nop 0
	v_addc_co_u32_e32 v81, vcc, 0, v69, vcc
	ds_write_b16_d16_hi v84, v67 offset:32960
	v_bfe_u32 v67, v75, 16, 1
	v_add_co_u32_e32 v80, vcc, 0x14000, v68
	v_add3_u32 v67, v75, v67, s33
	s_nop 0
	v_addc_co_u32_e32 v81, vcc, 0, v69, vcc
	ds_write_b16_d16_hi v84, v67 offset:33472
	v_bfe_u32 v67, v74, 16, 1
	v_add3_u32 v67, v74, v67, s33
	v_add_co_u32_e32 v74, vcc, 0x8000, v68
	v_pk_mul_f32 v[80:81], v[0:1], v[0:1]
	s_nop 0
	v_addc_co_u32_e32 v75, vcc, 0, v69, vcc
	ds_write_b16_d16_hi v84, v67 offset:33088
	v_bfe_u32 v67, v78, 16, 1
	v_add_co_u32_e32 v74, vcc, 0x18000, v68
	v_add3_u32 v67, v78, v67, s33
	s_nop 0
	v_addc_co_u32_e32 v75, vcc, 0, v69, vcc
	ds_write_b16_d16_hi v84, v67 offset:33600
	v_bfe_u32 v67, v73, 16, 1
	v_add_co_u32_e32 v72, vcc, 0xc000, v68
	v_add3_u32 v67, v73, v67, s33
	s_nop 0
	v_addc_co_u32_e32 v73, vcc, 0, v69, vcc
	ds_write_b16_d16_hi v84, v67 offset:33216
	v_bfe_u32 v67, v77, 16, 1
	v_add_co_u32_e32 v68, vcc, 0x1c000, v68
	v_add3_u32 v67, v77, v67, s33
	s_nop 0
	v_addc_co_u32_e32 v69, vcc, 0, v69, vcc
	ds_write_b16_d16_hi v84, v67 offset:33728
	v_and_b32_e32 v69, 0x7fffffff, v5
	v_and_b32_e32 v68, 0x7fffffff, v4
	v_pk_fma_f32 v[68:69], v[68:69], s[90:91], 1.0 op_sel_hi:[1,0,0]
	v_mov_b64_e32 v[76:77], s[16:17]
	v_rcp_f32_e32 v68, v68
	v_rcp_f32_e32 v69, v69
	v_pk_mul_f32 v[74:75], v[4:5], v[4:5]
	v_cmp_gt_f32_e32 vcc, 0, v4
	v_pk_mul_f32 v[74:75], v[74:75], s[66:67] op_sel_hi:[1,0]
	v_pk_fma_f32 v[72:73], v[68:69], s[92:93], v[76:77] op_sel_hi:[1,0,0]
	v_exp_f32_e32 v74, v74
	v_pk_fma_f32 v[72:73], v[68:69], v[72:73], s[96:97] op_sel_hi:[1,1,0]
	v_exp_f32_e32 v75, v75
	v_pk_fma_f32 v[72:73], v[68:69], v[72:73], s[12:13] op_sel_hi:[1,1,0]
	v_pk_mul_f32 v[80:81], v[80:81], s[66:67] op_sel_hi:[1,0]
	v_pk_fma_f32 v[72:73], v[68:69], v[72:73], s[14:15] op_sel_hi:[1,1,0]
	v_exp_f32_e32 v80, v80
	v_pk_mul_f32 v[68:69], v[68:69], v[72:73]
	v_pk_mul_f32 v[72:73], v[6:7], v[6:7]
	v_pk_mul_f32 v[68:69], v[74:75], v[68:69]
	v_pk_mul_f32 v[72:73], v[72:73], s[66:67] op_sel_hi:[1,0]
	v_pk_mul_f32 v[74:75], v[4:5], v[68:69]
	v_pk_fma_f32 v[78:79], v[4:5], v[68:69], v[4:5] neg_lo:[1,0,0] neg_hi:[1,0,0]
	v_exp_f32_e32 v72, v72
	v_cndmask_b32_e32 v69, v78, v74, vcc
	v_cmp_gt_f32_e32 vcc, 0, v5
	v_and_b32_e32 v74, 0x7fffffff, v6
	v_exp_f32_e32 v73, v73
	v_cndmask_b32_e32 v68, v79, v75, vcc
	v_and_b32_e32 v75, 0x7fffffff, v7
	v_pk_fma_f32 v[74:75], v[74:75], s[90:91], 1.0 op_sel_hi:[1,0,0]
	v_cmp_gt_f32_e32 vcc, 0, v6
	v_rcp_f32_e32 v74, v74
	v_rcp_f32_e32 v75, v75
	v_exp_f32_e32 v81, v81
	v_mul_f32_e32 v67, v68, v68
	v_fmac_f32_e32 v67, v69, v69
	v_pk_fma_f32 v[78:79], v[74:75], s[92:93], v[76:77] op_sel_hi:[1,0,0]
	v_add_u32_e32 v66, 0xb0, v66
	v_pk_fma_f32 v[78:79], v[74:75], v[78:79], s[96:97] op_sel_hi:[1,1,0]
	s_nop 0
	v_pk_fma_f32 v[78:79], v[74:75], v[78:79], s[12:13] op_sel_hi:[1,1,0]
	s_nop 0
	v_pk_fma_f32 v[78:79], v[74:75], v[78:79], s[14:15] op_sel_hi:[1,1,0]
	s_nop 0
	v_pk_mul_f32 v[74:75], v[74:75], v[78:79]
	s_nop 0
	v_pk_mul_f32 v[72:73], v[72:73], v[74:75]
	s_nop 0
	v_pk_mul_f32 v[74:75], v[6:7], v[72:73]
	v_pk_fma_f32 v[78:79], v[6:7], v[72:73], v[6:7] neg_lo:[1,0,0] neg_hi:[1,0,0]
	s_nop 0
	v_cndmask_b32_e32 v73, v78, v74, vcc
	v_cmp_gt_f32_e32 vcc, 0, v7
	v_and_b32_e32 v74, 0x7fffffff, v0
	s_nop 0
	v_cndmask_b32_e32 v72, v79, v75, vcc
	v_and_b32_e32 v75, 0x7fffffff, v1
	v_pk_fma_f32 v[74:75], v[74:75], s[90:91], 1.0 op_sel_hi:[1,0,0]
	v_cmp_gt_f32_e32 vcc, 0, v0
	v_rcp_f32_e32 v74, v74
	v_rcp_f32_e32 v75, v75
	s_nop 0
	v_pk_fma_f32 v[78:79], v[74:75], s[92:93], v[76:77] op_sel_hi:[1,0,0]
	s_nop 0
	v_pk_fma_f32 v[78:79], v[74:75], v[78:79], s[96:97] op_sel_hi:[1,1,0]
	s_nop 0
	v_pk_fma_f32 v[78:79], v[74:75], v[78:79], s[12:13] op_sel_hi:[1,1,0]
	s_nop 0
	v_pk_fma_f32 v[78:79], v[74:75], v[78:79], s[14:15] op_sel_hi:[1,1,0]
	s_nop 0
	v_pk_mul_f32 v[74:75], v[74:75], v[78:79]
	v_pk_mul_f32 v[78:79], v[2:3], v[2:3]
	v_pk_mul_f32 v[74:75], v[80:81], v[74:75]
	v_pk_mul_f32 v[78:79], v[78:79], s[66:67] op_sel_hi:[1,0]
	v_pk_mul_f32 v[80:81], v[0:1], v[74:75]
	v_pk_fma_f32 v[82:83], v[0:1], v[74:75], v[0:1] neg_lo:[1,0,0] neg_hi:[1,0,0]
	v_exp_f32_e32 v78, v78
	v_cndmask_b32_e32 v75, v82, v80, vcc
	v_cmp_gt_f32_e32 vcc, 0, v1
	v_and_b32_e32 v80, 0x7fffffff, v2
	v_exp_f32_e32 v79, v79
	v_cndmask_b32_e32 v74, v83, v81, vcc
	v_and_b32_e32 v81, 0x7fffffff, v3
	v_pk_fma_f32 v[80:81], v[80:81], s[90:91], 1.0 op_sel_hi:[1,0,0]
	v_cmp_gt_f32_e32 vcc, 0, v2
	v_rcp_f32_e32 v80, v80
	v_rcp_f32_e32 v81, v81
	s_nop 0
	v_pk_fma_f32 v[76:77], v[80:81], s[92:93], v[76:77] op_sel_hi:[1,0,0]
	s_nop 0
	v_pk_fma_f32 v[76:77], v[80:81], v[76:77], s[96:97] op_sel_hi:[1,1,0]
	s_nop 0
	v_pk_fma_f32 v[76:77], v[80:81], v[76:77], s[12:13] op_sel_hi:[1,1,0]
	s_nop 0
	v_pk_fma_f32 v[76:77], v[80:81], v[76:77], s[14:15] op_sel_hi:[1,1,0]
	s_nop 0
	v_pk_mul_f32 v[76:77], v[80:81], v[76:77]
	s_nop 0
	v_pk_mul_f32 v[76:77], v[78:79], v[76:77]
	s_nop 0
	v_pk_mul_f32 v[78:79], v[2:3], v[76:77]
	v_pk_fma_f32 v[80:81], v[2:3], v[76:77], v[2:3] neg_lo:[1,0,0] neg_hi:[1,0,0]
	s_nop 0
	v_cndmask_b32_e32 v77, v80, v78, vcc
	v_cmp_gt_f32_e32 vcc, 0, v3
	v_mul_f32_e32 v78, v72, v72
	v_fmac_f32_e32 v78, v73, v73
	v_cndmask_b32_e32 v76, v81, v79, vcc
	v_add_f32_e32 v67, v67, v78
	v_mul_f32_e32 v78, v74, v74
	v_mul_f32_e32 v79, v76, v76
	v_fmac_f32_e32 v78, v75, v75
	v_fmac_f32_e32 v79, v77, v77
	v_add_f32_e32 v78, v78, v79
	v_add_f32_e32 v67, v67, v78
	ds_bpermute_b32 v70, v70, v67
	s_waitcnt lgkmcnt(0)
	v_add_f32_e32 v70, v67, v70
	ds_bpermute_b32 v71, v71, v70
	v_ashrrev_i32_e32 v67, 31, v66
	s_and_saveexec_b64 s[2:3], s[4:5]
	s_xor_b64 s[2:3], exec, s[2:3]
	s_mov_b32 s48, 0xbf3a00e3
	s_andn2_saveexec_b64 s[2:3], s[2:3]
	s_cbranch_execz .LBB0_549
	s_waitcnt lgkmcnt(0)
	v_add_f32_e32 v78, v70, v71
	v_mov_b64_e32 v[70:71], s[8:9]
	v_mad_i64_i32 v[70:71], s[8:9], v66, s18, v[70:71]
	s_lshl_b32 s80, s15, 2
	v_lshl_add_u64 v[70:71], v[70:71], 0, s[80:81]
	global_store_dword v[70:71], v78, off offset:80
.LBB0_549:
	s_or_b64 exec, exec, s[2:3]
	v_lshl_add_u64 v[64:65], v[66:67], 1, v[64:65]
	v_bfe_u32 v66, v69, 16, 1
	v_add3_u32 v66, v69, v66, s33
	ds_write_b16_d16_hi v84, v66 offset:32864
	v_bfe_u32 v66, v75, 16, 1
	v_add3_u32 v69, v75, v66, s33
	v_add_co_u32_e32 v66, vcc, 0x10000, v64
	s_nop 1
	v_addc_co_u32_e32 v67, vcc, 0, v65, vcc
	ds_write_b16_d16_hi v84, v69 offset:33376
	v_bfe_u32 v66, v68, 16, 1
	v_add3_u32 v68, v68, v66, s33
	v_add_co_u32_e32 v66, vcc, 0x4000, v64
	s_nop 1
	v_addc_co_u32_e32 v67, vcc, 0, v65, vcc
	ds_write_b16_d16_hi v84, v68 offset:32992
	v_bfe_u32 v66, v74, 16, 1
	v_add3_u32 v68, v74, v66, s33
	v_add_co_u32_e32 v66, vcc, 0x14000, v64
	s_nop 1
	v_addc_co_u32_e32 v67, vcc, 0, v65, vcc
	ds_write_b16_d16_hi v84, v68 offset:33504
	v_bfe_u32 v66, v73, 16, 1
	v_add3_u32 v68, v73, v66, s33
	v_add_co_u32_e32 v66, vcc, 0x8000, v64
	s_nop 1
	v_addc_co_u32_e32 v67, vcc, 0, v65, vcc
	ds_write_b16_d16_hi v84, v68 offset:33120
	v_bfe_u32 v66, v77, 16, 1
	v_add3_u32 v68, v77, v66, s33
	v_add_co_u32_e32 v66, vcc, 0x18000, v64
	s_nop 1
	v_addc_co_u32_e32 v67, vcc, 0, v65, vcc
	ds_write_b16_d16_hi v84, v68 offset:33632
	v_bfe_u32 v66, v72, 16, 1
	v_add3_u32 v68, v72, v66, s33
	v_add_co_u32_e32 v66, vcc, 0xc000, v64
	s_nop 1
	v_addc_co_u32_e32 v67, vcc, 0, v65, vcc
	ds_write_b16_d16_hi v84, v68 offset:33248
	v_bfe_u32 v66, v76, 16, 1
	v_add_co_u32_e32 v64, vcc, 0x1c000, v64
	v_add3_u32 v66, v76, v66, s33
	s_nop 0
	v_addc_co_u32_e32 v65, vcc, 0, v65, vcc
	ds_write_b16_d16_hi v84, v66 offset:33760
	s_waitcnt lgkmcnt(0)
	v_lshrrev_b32_e32 v86, 6, v215
	v_lshlrev_b32_e32 v85, 4, v214
	v_lshl_add_u32 v85, v86, 10, v85
	ds_read_b128 v[88:91], v85
	ds_read_b128 v[92:95], v85 offset:8192
	ds_read_b128 v[96:99], v85 offset:16384
	ds_read_b128 v[100:103], v85 offset:24576
	ds_read_b128 v[104:107], v85 offset:32768
	ds_read_b128 v[108:111], v85 offset:40960
	ds_read_b128 v[112:115], v85 offset:49152
	ds_read_b128 v[116:119], v85 offset:57344
	s_add_u32 s34, s74, 0x4b00000
	s_addc_u32 s35, s75, 0
	s_sub_i32 s2, s54, 2
	s_lshl_b32 s2, s2, 7
	v_and_b32_e32 v87, 3, v86
	v_lshrrev_b32_e32 v121, 2, v86
	v_lshrrev_b32_e32 v122, 3, v214
	v_lshl_add_u32 v87, v87, 5, v122
	v_add_u32_e32 v87, s2, v87
	v_lshlrev_b32_e32 v87, 13, v87
	v_and_b32_e32 v122, 7, v214
	v_lshlrev_b32_e32 v122, 3, v122
	v_lshl_add_u32 v122, v121, 6, v122
	s_lshl_b32 s2, s10, 8
	v_add3_u32 v87, v87, v122, s2
	v_lshlrev_b32_e32 v87, 1, v87
	s_waitcnt lgkmcnt(7)
	global_store_dwordx4 v87, v[88:91], s[34:35]
	v_add_u32_e32 v120, 0x20000, v87
	s_waitcnt lgkmcnt(6)
	global_store_dwordx4 v120, v[92:95], s[34:35]
	v_add_u32_e32 v120, 0x40000, v87
	s_waitcnt lgkmcnt(5)
	global_store_dwordx4 v120, v[96:99], s[34:35]
	v_add_u32_e32 v120, 0x60000, v87
	s_waitcnt lgkmcnt(4)
	global_store_dwordx4 v120, v[100:103], s[34:35]
	v_add_u32_e32 v120, 0x100, v87
	s_waitcnt lgkmcnt(3)
	global_store_dwordx4 v120, v[104:107], s[34:35]
	v_add_u32_e32 v120, 0x20100, v87
	s_waitcnt lgkmcnt(2)
	global_store_dwordx4 v120, v[108:111], s[34:35]
	v_add_u32_e32 v120, 0x40100, v87
	s_waitcnt lgkmcnt(1)
	global_store_dwordx4 v120, v[112:115], s[34:35]
	v_add_u32_e32 v120, 0x60100, v87
	s_waitcnt lgkmcnt(0)
	global_store_dwordx4 v120, v[116:119], s[34:35]
